# adds: batched census loads (throttled retry) and the post-barrier L1 invalidate moved to overlap the arrival atomic
# speedup vs baseline: 1.0017x; 1.0017x over previous
; __device__ __forceinline__ unsigned xb_ld(unsigned* p)              { return __hip_atomic_load(p, __ATOMIC_RELAXED, __HIP_MEMORY_SCOPE_AGENT); }
; __device__ __forceinline__ void xcd_barrier_complete(unsigned* bar, unsigned x, unsigned& nloc, unsigned& nx) {
;     ...
;     unsigned sum, cnt, mine, sp = 0u;
;     for (;;) {
;         sum = 0u; cnt = 0u; mine = 0u;
; #pragma unroll
;         for (unsigned j = 0; j < 16; ++j) { const unsigned c = xb_ld(&bar[XB_XCNT(j)]); sum += c; cnt += (c > 0u) ? 1u : 0u; mine = (j == x) ? c : mine; }
;         if (sum == G) break;
;         __builtin_amdgcn_s_sleep(1);
;         if ((++sp & 255u) == 0u) { if (xb_ld(&bar[XB_TMO])) break; if (sp > XB_SPIN_CAP) { atomicAdd(&bar[XB_TMO], 1u); break; } }
;     }
;     nloc = mine > 0u ? mine : 1u; nx = cnt > 0u ? cnt : 1u;
.LBB0_812:
	v_mov_b64_e32 v[22:23], s[2:3]
	v_mov_b64_e32 v[24:25], s[24:25]
	v_mov_b64_e32 v[26:27], s[26:27]
	v_mov_b64_e32 v[28:29], s[30:31]
	v_mov_b64_e32 v[30:31], s[36:37]
	s_waitcnt lgkmcnt(0)
	global_load_dword v2, v[22:23], off offset:1024 sc1
	global_load_dword v0, v[22:23], off offset:1280 sc1
	global_load_dword v3, v[22:23], off offset:1536 sc1
	global_load_dword v4, v[22:23], off offset:1792 sc1
	global_load_dword v5, v[22:23], off offset:2048 sc1
	global_load_dword v6, v[22:23], off offset:2304 sc1
	global_load_dword v7, v[22:23], off offset:2560 sc1
	global_load_dword v8, v[22:23], off offset:2816 sc1
	global_load_dword v9, v[22:23], off offset:3072 sc1
	global_load_dword v10, v[22:23], off offset:3328 sc1
	global_load_dword v11, v[22:23], off offset:3584 sc1
	global_load_dword v12, v[22:23], off offset:3840 sc1
	global_load_dword v13, v[24:25], off sc1
	global_load_dword v14, v[26:27], off sc1
	global_load_dword v15, v[28:29], off sc1
	global_load_dword v16, v[30:31], off sc1
	v_readlane_b32 s4, v247, 47
	s_or_b64 s[44:45], s[44:45], exec
	s_or_b64 s[42:43], s[42:43], exec
	s_waitcnt vmcnt(0) lgkmcnt(0)
	v_add_u32_e32 v17, v0, v2
	v_add_u32_e32 v17, v17, v3
	v_add_u32_e32 v17, v17, v4
	v_add_u32_e32 v17, v17, v5
	v_add_u32_e32 v17, v17, v6
	v_add_u32_e32 v17, v17, v7
	v_add_u32_e32 v17, v17, v8
	v_add_u32_e32 v17, v17, v9
	v_add_u32_e32 v17, v17, v10
	v_add_u32_e32 v17, v17, v11
	v_add_u32_e32 v17, v17, v12
	v_add_u32_e32 v17, v17, v13
	v_add_u32_e32 v17, v17, v14
	v_add_u32_e32 v17, v17, v15
	v_add_u32_e32 v17, v17, v16
	v_cmp_ne_u32_e32 vcc, s4, v17
	s_and_saveexec_b64 s[46:47], vcc
	s_cbranch_execz .LBB0_811
	s_and_b32 s4, s7, 0xff
	s_mov_b64 s[48:49], -1
	s_cmp_eq_u32 s4, 0
	s_mov_b64 s[52:53], -1
	s_mov_b64 s[50:51], -1
	s_sleep 10
	s_cbranch_scc1 .LBB0_815
	s_and_saveexec_b64 s[4:5], s[52:53]
	s_cbranch_execz .LBB0_810
	s_branch .LBB0_818

; __device__ __forceinline__ unsigned xb_ld(unsigned* p)              { return __hip_atomic_load(p, __ATOMIC_RELAXED, __HIP_MEMORY_SCOPE_AGENT); }
; __device__ __forceinline__ unsigned xb_add(unsigned* p, unsigned v) { return __hip_atomic_fetch_add(p, v, __ATOMIC_RELAXED, __HIP_MEMORY_SCOPE_AGENT); }
; #define XB_SPIN(cond, bar) do { unsigned _sp = 0; while (cond) { __builtin_amdgcn_s_sleep(1); \
;     if ((++_sp & 255u) == 0u) { if (xb_ld(&(bar)[XB_TMO])) break; if (_sp > XB_SPIN_CAP) { atomicAdd(&(bar)[XB_TMO], 1u); break; } } } } while (0)
; __device__ __forceinline__ void xcd_barrier(const XcdBarrier& b) {
;     asm volatile("s_waitcnt vmcnt(0)" ::: "memory");
;     __syncthreads();
;     if (threadIdx.x == 0) {
;         unsigned* bar = b.bar; asm volatile("" : "+s"(bar));
;         __builtin_amdgcn_s_waitcnt(0);
;         unsigned nloc = b.st[0], nx = b.st[1];
;         if (nloc == 0u) { xcd_barrier_complete(bar, b.x, nloc, nx); b.st[0] = nloc; b.st[1] = nx; }
;         const unsigned old = xb_add(&bar[XB_XSUB(b.x)], 1u);
;         const unsigned gen = old / nloc;
;         if (old + 1u == (gen + 1u) * nloc) {
;             __builtin_amdgcn_fence(__ATOMIC_RELEASE, "agent");
;             asm volatile("s_waitcnt vmcnt(0)" ::: "memory");
;             const unsigned og = xb_add(&bar[XB_TOP], 1u);
;             const unsigned tg = og / nx;
;             if (og + 1u == (tg + 1u) * nx) xb_add(&bar[XB_TOPGEN], 1u);
;             else XB_SPIN(xb_ld(&bar[XB_TOPGEN]) == tg, bar);
;             __builtin_amdgcn_fence(__ATOMIC_ACQUIRE, "agent");
;             asm volatile("s_waitcnt vmcnt(0)" ::: "memory");
;         } else {
;             XB_SPIN(xb_ld(&bar[XB_TOPGEN]) == gen, bar);
.LBB0_822:
	v_readlane_b32 s4, v246, 51
	s_add_u32 s4, s2, s4
	s_addc_u32 s5, s3, 0
	v_mov_b32_e32 v3, s4
	v_add_co_u32_e32 v4, vcc, 0x1000, v3
	v_mov_b32_e32 v3, s5
	s_nop 0
	v_addc_co_u32_e32 v5, vcc, 0, v3, vcc
	buffer_inv sc1
	flat_atomic_add v4, v[4:5], v210 offset:1024 sc0
	v_cvt_f32_u32_e32 v3, v2
	v_sub_u32_e32 v5, 0, v2
	v_rcp_iflag_f32_e32 v3, v3
	s_nop 0
	v_mul_f32_e32 v3, 0x4f7ffffe, v3
	v_cvt_u32_f32_e32 v3, v3
	v_mul_lo_u32 v5, v5, v3
	v_mul_hi_u32 v5, v3, v5
	v_add_u32_e32 v3, v3, v5
	s_waitcnt vmcnt(0) lgkmcnt(0)
	v_mul_hi_u32 v3, v4, v3
	v_mul_lo_u32 v5, v3, v2
	v_sub_u32_e32 v5, v4, v5
	v_cmp_ge_u32_e32 vcc, v5, v2
	v_add_u32_e32 v6, 1, v3
	s_nop 0
	v_cndmask_b32_e32 v3, v3, v6, vcc
	v_sub_u32_e32 v6, v5, v2
	v_cndmask_b32_e32 v5, v5, v6, vcc
	v_cmp_ge_u32_e32 vcc, v5, v2
	v_add_u32_e32 v5, 1, v3
	v_add_u32_e32 v6, 1, v4
	v_cndmask_b32_e32 v3, v3, v5, vcc
	v_mad_u64_u32 v[4:5], s[4:5], v2, v3, v[2:3]
	v_cmp_ne_u32_e32 vcc, v6, v4
	s_and_saveexec_b64 s[4:5], vcc
	s_xor_b64 s[24:25], exec, s[4:5]
	s_cbranch_execz .LBB0_835
	v_mad_u32_u24 v20, v3, v0, v0
	v_mov_b32_e32 v0, s2
	v_add_co_u32_e32 v4, vcc, 0x3000, v0
	v_mov_b32_e32 v0, s3
	s_nop 0
	v_addc_co_u32_e32 v5, vcc, 0, v0, vcc
	flat_load_dword v0, v[4:5] offset:1024 sc1
	s_add_u32 s30, s2, 0x3500
	s_addc_u32 s31, s3, 0
	s_waitcnt vmcnt(0) lgkmcnt(0)
	v_cmp_lt_u32_e32 vcc, v0, v20
	s_and_saveexec_b64 s[26:27], vcc
	s_cbranch_execz .LBB0_834
	s_mov_b32 s4, 1
	s_mov_b64 s[36:37], 0
	s_branch .LBB0_826

; __device__ __forceinline__ unsigned xb_ld(unsigned* p)              { return __hip_atomic_load(p, __ATOMIC_RELAXED, __HIP_MEMORY_SCOPE_AGENT); }
; #define XB_SPIN(cond, bar) do { unsigned _sp = 0; while (cond) { __builtin_amdgcn_s_sleep(1); \
;     if ((++_sp & 255u) == 0u) { if (xb_ld(&(bar)[XB_TMO])) break; if (_sp > XB_SPIN_CAP) { atomicAdd(&(bar)[XB_TMO], 1u); break; } } } } while (0)
; __device__ __forceinline__ void xcd_barrier(const XcdBarrier& b) {
;     ...
;             __builtin_amdgcn_fence(__ATOMIC_ACQUIRE, "agent");
;             asm volatile("s_waitcnt vmcnt(0)" ::: "memory");
;         } else {
;             XB_SPIN(xb_ld(&bar[XB_TOPGEN]) == gen, bar);
;             __builtin_amdgcn_fence(__ATOMIC_ACQUIRE, "agent");
;             asm volatile("s_waitcnt vmcnt(0)" ::: "memory");
.LBB0_834:
	s_or_b64 exec, exec, s[26:27]
	s_waitcnt vmcnt(0) lgkmcnt(0)
	s_waitcnt vmcnt(0)

; __device__ __forceinline__ unsigned xb_ld(unsigned* p)              { return __hip_atomic_load(p, __ATOMIC_RELAXED, __HIP_MEMORY_SCOPE_AGENT); }
; __device__ __forceinline__ unsigned xb_add(unsigned* p, unsigned v) { return __hip_atomic_fetch_add(p, v, __ATOMIC_RELAXED, __HIP_MEMORY_SCOPE_AGENT); }
; #define XB_SPIN(cond, bar) do { unsigned _sp = 0; while (cond) { __builtin_amdgcn_s_sleep(1); \
;     if ((++_sp & 255u) == 0u) { if (xb_ld(&(bar)[XB_TMO])) break; if (_sp > XB_SPIN_CAP) { atomicAdd(&(bar)[XB_TMO], 1u); break; } } } } while (0)
; __device__ __forceinline__ void xcd_barrier(const XcdBarrier& b) {
;     ...
;             __builtin_amdgcn_fence(__ATOMIC_RELEASE, "agent");
;             asm volatile("s_waitcnt vmcnt(0)" ::: "memory");
;             const unsigned og = xb_add(&bar[XB_TOP], 1u);
;             const unsigned tg = og / nx;
;             if (og + 1u == (tg + 1u) * nx) xb_add(&bar[XB_TOPGEN], 1u);
;             else XB_SPIN(xb_ld(&bar[XB_TOPGEN]) == tg, bar);
;             __builtin_amdgcn_fence(__ATOMIC_ACQUIRE, "agent");
;             asm volatile("s_waitcnt vmcnt(0)" ::: "memory");
.LBB0_850:
	s_or_b64 exec, exec, s[2:3]
	s_waitcnt vmcnt(0) lgkmcnt(0)
	s_waitcnt vmcnt(0)
